# v41 + P12 epilogue operands (shift rows, rstd) requested in the last K-iteration with the second-segment wait counting them in (vmcnt(18) there); epilogue no longer starts with loads + vmcnt(0)
# speedup vs baseline: 1.0040x; 1.0040x over previous
.LBB0_3264:
	s_ashr_i32 s11, s10, 31
	v_cmp_lt_i64_e32 vcc, s[12:13], v[162:163]
	s_lshl_b64 s[12:13], s[10:11], 19
	s_add_u32 s12, s36, s12
	s_addc_u32 s13, s37, s13
	s_and_b64 s[14:15], vcc, exec
	s_cselect_b32 s11, s13, s25
	s_cselect_b32 s57, s12, s24
	s_ashr_i32 s9, s8, 31
	s_lshl_b64 s[14:15], s[8:9], 19
	s_add_u32 s14, s38, s14
	s_addc_u32 s15, s39, s15
	s_and_b64 s[18:19], vcc, exec
	s_cselect_b32 s9, s15, s35
	s_cselect_b32 s60, s14, s34
	s_add_u32 s24, s24, 0x40080
	s_addc_u32 s25, s25, 0
	s_add_u32 s61, s34, 0x100
	s_addc_u32 s62, s35, 0
	s_mov_b32 s63, -2
	ds_read_b128 v[130:133], v171
	ds_read_b128 v[134:137], v171 offset:1024
	ds_read_b128 v[138:141], v171 offset:2048
	ds_read_b128 v[142:145], v171 offset:3072
	s_add_u32 s18, s24, 0xfffc0080
	s_addc_u32 s19, s25, -1
	s_cmp_eq_u32 s63, 12
	s_cselect_b32 s19, s11, s19
	s_cselect_b32 s18, s57, s18
	s_cselect_b32 s35, s9, s62
	s_cselect_b32 s34, s60, s61
	v_lshl_add_u64 v[174:175], s[24:25], 0, v[158:159]
	s_add_i32 m0, s43, 0xc000
	ds_read_b128 v[166:169], v173
	ds_read_b128 v[178:181], v173 offset:1024
	ds_read_b128 v[182:185], v173 offset:2048
	ds_read_b128 v[186:189], v173 offset:3072
	ds_read_b128 v[190:193], v173 offset:4096
	ds_read_b128 v[194:197], v173 offset:5120
	ds_read_b128 v[198:201], v173 offset:6144
	ds_read_b128 v[202:205], v173 offset:7168
	global_load_lds_dwordx4 v[174:175], off
	v_lshl_add_u64 v[174:175], s[24:25], 0, v[160:161]
	s_add_i32 m0, s43, 0xe000
	s_nop 0
	global_load_lds_dwordx4 v[174:175], off
	ds_read_b128 v[206:209], v177
	ds_read_b128 v[210:213], v177 offset:1024
	ds_read_b128 v[214:217], v177 offset:2048
	ds_read_b128 v[218:221], v177 offset:3072
	s_waitcnt lgkmcnt(0)
	s_setprio 1
	s_barrier
	v_mfma_f32_16x16x32_bf16 v[126:129], v[130:133], v[166:169], 0
	v_mfma_f32_16x16x32_bf16 v[122:125], v[138:141], v[166:169], 0
	v_mfma_f32_16x16x32_bf16 v[110:113], v[130:133], v[182:185], 0
	v_mfma_f32_16x16x32_bf16 v[106:109], v[138:141], v[182:185], 0
	v_mfma_f32_16x16x32_bf16 v[94:97], v[130:133], v[190:193], 0
	v_mfma_f32_16x16x32_bf16 v[90:93], v[138:141], v[190:193], 0
	v_mfma_f32_16x16x32_bf16 v[78:81], v[130:133], v[198:201], 0
	v_mfma_f32_16x16x32_bf16 v[74:77], v[138:141], v[198:201], 0
	v_mfma_f32_16x16x32_bf16 v[126:129], v[134:137], v[178:181], v[126:129]
	v_mfma_f32_16x16x32_bf16 v[122:125], v[142:145], v[178:181], v[122:125]
	v_mfma_f32_16x16x32_bf16 v[110:113], v[134:137], v[186:189], v[110:113]
	v_mfma_f32_16x16x32_bf16 v[106:109], v[142:145], v[186:189], v[106:109]
	v_mfma_f32_16x16x32_bf16 v[94:97], v[134:137], v[194:197], v[94:97]
	v_mfma_f32_16x16x32_bf16 v[90:93], v[142:145], v[194:197], v[90:93]
	v_mfma_f32_16x16x32_bf16 v[78:81], v[134:137], v[202:205], v[78:81]
	v_mfma_f32_16x16x32_bf16 v[74:77], v[142:145], v[202:205], v[74:77]
	v_mfma_f32_16x16x32_bf16 v[118:121], v[206:209], v[166:169], 0
	v_mfma_f32_16x16x32_bf16 v[114:117], v[214:217], v[166:169], 0
	v_mfma_f32_16x16x32_bf16 v[102:105], v[206:209], v[182:185], 0
	v_mfma_f32_16x16x32_bf16 v[98:101], v[214:217], v[182:185], 0
	v_mfma_f32_16x16x32_bf16 v[86:89], v[206:209], v[190:193], 0
	v_mfma_f32_16x16x32_bf16 v[82:85], v[214:217], v[190:193], 0
	v_mfma_f32_16x16x32_bf16 v[70:73], v[206:209], v[198:201], 0
	v_mfma_f32_16x16x32_bf16 v[66:69], v[214:217], v[198:201], 0
	v_mfma_f32_16x16x32_bf16 v[118:121], v[210:213], v[178:181], v[118:121]
	v_mfma_f32_16x16x32_bf16 v[114:117], v[218:221], v[178:181], v[114:117]
	v_mfma_f32_16x16x32_bf16 v[102:105], v[210:213], v[186:189], v[102:105]
	v_mfma_f32_16x16x32_bf16 v[98:101], v[218:221], v[186:189], v[98:101]
	v_mfma_f32_16x16x32_bf16 v[86:89], v[210:213], v[194:197], v[86:89]
	v_mfma_f32_16x16x32_bf16 v[82:85], v[218:221], v[194:197], v[82:85]
	v_mfma_f32_16x16x32_bf16 v[70:73], v[210:213], v[202:205], v[70:73]
	v_mfma_f32_16x16x32_bf16 v[66:69], v[218:221], v[202:205], v[66:69]
	s_barrier
	s_setprio 0
	s_add_i32 s20, s54, s42
	v_lshl_add_u64 v[174:175], s[34:35], 0, v[150:151]
	s_mov_b32 m0, s20
	s_nop 0
	global_load_lds_dwordx4 v[174:175], off
	v_lshl_add_u64 v[222:223], s[34:35], 0, v[146:147]
	s_add_i32 m0, s20, 0x2000
	s_nop 0
	global_load_lds_dwordx4 v[222:223], off
	s_mov_b32 m0, s43
	v_lshl_add_u64 v[224:225], s[18:19], 0, v[152:153]
	ds_read_b128 v[166:169], v173 offset:16384
	ds_read_b128 v[178:181], v173 offset:17408
	ds_read_b128 v[182:185], v173 offset:18432
	ds_read_b128 v[186:189], v173 offset:19456
	ds_read_b128 v[190:193], v173 offset:20480
	ds_read_b128 v[194:197], v173 offset:21504
	ds_read_b128 v[198:201], v173 offset:22528
	ds_read_b128 v[202:205], v173 offset:23552
	global_load_lds_dwordx4 v[224:225], off
	v_lshl_add_u64 v[226:227], s[18:19], 0, v[148:149]
	s_mov_b32 m0, s44
	s_nop 0
	global_load_lds_dwordx4 v[226:227], off
	s_waitcnt vmcnt(6)
	s_waitcnt lgkmcnt(0)
	s_setprio 1
	s_barrier
	v_mfma_f32_16x16x32_bf16 v[62:65], v[130:133], v[166:169], 0
	v_mfma_f32_16x16x32_bf16 v[58:61], v[138:141], v[166:169], 0
	v_mfma_f32_16x16x32_bf16 v[46:49], v[130:133], v[182:185], 0
	v_mfma_f32_16x16x32_bf16 v[42:45], v[138:141], v[182:185], 0
	v_mfma_f32_16x16x32_bf16 v[30:33], v[130:133], v[190:193], 0
	v_mfma_f32_16x16x32_bf16 v[26:29], v[138:141], v[190:193], 0
	v_mfma_f32_16x16x32_bf16 v[14:17], v[130:133], v[198:201], 0
	v_mfma_f32_16x16x32_bf16 v[10:13], v[138:141], v[198:201], 0
	v_mfma_f32_16x16x32_bf16 v[62:65], v[134:137], v[178:181], v[62:65]
	v_mfma_f32_16x16x32_bf16 v[58:61], v[142:145], v[178:181], v[58:61]
	v_mfma_f32_16x16x32_bf16 v[46:49], v[134:137], v[186:189], v[46:49]
	v_mfma_f32_16x16x32_bf16 v[42:45], v[142:145], v[186:189], v[42:45]
	v_mfma_f32_16x16x32_bf16 v[30:33], v[134:137], v[194:197], v[30:33]
	v_mfma_f32_16x16x32_bf16 v[26:29], v[142:145], v[194:197], v[26:29]
	v_mfma_f32_16x16x32_bf16 v[14:17], v[134:137], v[202:205], v[14:17]
	v_mfma_f32_16x16x32_bf16 v[10:13], v[142:145], v[202:205], v[10:13]
	v_mfma_f32_16x16x32_bf16 v[54:57], v[206:209], v[166:169], 0
	v_mfma_f32_16x16x32_bf16 v[50:53], v[214:217], v[166:169], 0
	v_mfma_f32_16x16x32_bf16 v[38:41], v[206:209], v[182:185], 0
	v_mfma_f32_16x16x32_bf16 v[34:37], v[214:217], v[182:185], 0
	v_mfma_f32_16x16x32_bf16 v[22:25], v[206:209], v[190:193], 0
	v_mfma_f32_16x16x32_bf16 v[18:21], v[214:217], v[190:193], 0
	v_mfma_f32_16x16x32_bf16 v[6:9], v[206:209], v[198:201], 0
	v_mfma_f32_16x16x32_bf16 v[2:5], v[214:217], v[198:201], 0
	v_mfma_f32_16x16x32_bf16 v[54:57], v[210:213], v[178:181], v[54:57]
	v_mfma_f32_16x16x32_bf16 v[50:53], v[218:221], v[178:181], v[50:53]
	v_mfma_f32_16x16x32_bf16 v[38:41], v[210:213], v[186:189], v[38:41]
	v_mfma_f32_16x16x32_bf16 v[34:37], v[218:221], v[186:189], v[34:37]
	v_mfma_f32_16x16x32_bf16 v[22:25], v[210:213], v[194:197], v[22:25]
	v_mfma_f32_16x16x32_bf16 v[18:21], v[218:221], v[194:197], v[18:21]
	v_mfma_f32_16x16x32_bf16 v[6:9], v[210:213], v[202:205], v[6:9]
	v_mfma_f32_16x16x32_bf16 v[2:5], v[218:221], v[202:205], v[2:5]
	s_barrier
	s_setprio 0
	s_add_u32 s20, s34, 0x40000
	s_addc_u32 s21, s35, 0
	s_add_i32 s64, s55, s42
	v_lshl_add_u64 v[252:253], s[20:21], 0, v[150:151]
	s_mov_b32 m0, s64
	s_nop 0
	global_load_lds_dwordx4 v[252:253], off
	v_lshl_add_u64 v[252:253], s[20:21], 0, v[146:147]
	s_add_i32 m0, s64, 0x2000
	s_nop 0
	global_load_lds_dwordx4 v[252:253], off
	s_add_i32 s20, 0, 0x18000
	v_add_u32_e32 v142, s20, v157
	ds_read_b128 v[130:133], v142
	ds_read_b128 v[134:137], v142 offset:1024
	ds_read_b128 v[138:141], v142 offset:2048
	ds_read_b128 v[142:145], v142 offset:3072
	s_add_u32 s18, s18, 0x40000
	s_addc_u32 s19, s19, 0
	s_mov_b32 m0, s45
	v_lshl_add_u64 v[206:207], s[18:19], 0, v[152:153]
	ds_read_b128 v[166:169], v173 offset:32768
	ds_read_b128 v[178:181], v173 offset:33792
	ds_read_b128 v[182:185], v173 offset:34816
	ds_read_b128 v[186:189], v173 offset:35840
	ds_read_b128 v[190:193], v173 offset:36864
	ds_read_b128 v[194:197], v173 offset:37888
	ds_read_b128 v[198:201], v173 offset:38912
	ds_read_b128 v[202:205], v173 offset:39936
	global_load_lds_dwordx4 v[206:207], off
	v_lshl_add_u64 v[206:207], s[18:19], 0, v[148:149]
	s_mov_b32 m0, s46
	s_nop 0
	global_load_lds_dwordx4 v[206:207], off
	s_add_i32 s21, 0, 0x1c000
	v_add_u32_e32 v154, s21, v157
	ds_read_b128 v[206:209], v154
	ds_read_b128 v[210:213], v154 offset:1024
	ds_read_b128 v[214:217], v154 offset:2048
	ds_read_b128 v[218:221], v154 offset:3072
	s_waitcnt vmcnt(8)
	s_waitcnt lgkmcnt(0)
	s_setprio 1
	s_barrier
	v_mfma_f32_16x16x32_bf16 v[126:129], v[130:133], v[166:169], v[126:129]
	v_mfma_f32_16x16x32_bf16 v[122:125], v[138:141], v[166:169], v[122:125]
	v_mfma_f32_16x16x32_bf16 v[110:113], v[130:133], v[182:185], v[110:113]
	v_mfma_f32_16x16x32_bf16 v[106:109], v[138:141], v[182:185], v[106:109]
	v_mfma_f32_16x16x32_bf16 v[94:97], v[130:133], v[190:193], v[94:97]
	v_mfma_f32_16x16x32_bf16 v[90:93], v[138:141], v[190:193], v[90:93]
	v_mfma_f32_16x16x32_bf16 v[78:81], v[130:133], v[198:201], v[78:81]
	v_mfma_f32_16x16x32_bf16 v[74:77], v[138:141], v[198:201], v[74:77]
	v_mfma_f32_16x16x32_bf16 v[126:129], v[134:137], v[178:181], v[126:129]
	v_mfma_f32_16x16x32_bf16 v[122:125], v[142:145], v[178:181], v[122:125]
	v_mfma_f32_16x16x32_bf16 v[110:113], v[134:137], v[186:189], v[110:113]
	v_mfma_f32_16x16x32_bf16 v[106:109], v[142:145], v[186:189], v[106:109]
	v_mfma_f32_16x16x32_bf16 v[94:97], v[134:137], v[194:197], v[94:97]
	v_mfma_f32_16x16x32_bf16 v[90:93], v[142:145], v[194:197], v[90:93]
	v_mfma_f32_16x16x32_bf16 v[78:81], v[134:137], v[202:205], v[78:81]
	v_mfma_f32_16x16x32_bf16 v[74:77], v[142:145], v[202:205], v[74:77]
	v_mfma_f32_16x16x32_bf16 v[118:121], v[206:209], v[166:169], v[118:121]
	v_mfma_f32_16x16x32_bf16 v[114:117], v[214:217], v[166:169], v[114:117]
	v_mfma_f32_16x16x32_bf16 v[102:105], v[206:209], v[182:185], v[102:105]
	v_mfma_f32_16x16x32_bf16 v[98:101], v[214:217], v[182:185], v[98:101]
	v_mfma_f32_16x16x32_bf16 v[86:89], v[206:209], v[190:193], v[86:89]
	v_mfma_f32_16x16x32_bf16 v[82:85], v[214:217], v[190:193], v[82:85]
	v_mfma_f32_16x16x32_bf16 v[70:73], v[206:209], v[198:201], v[70:73]
	v_mfma_f32_16x16x32_bf16 v[66:69], v[214:217], v[198:201], v[66:69]
	v_mfma_f32_16x16x32_bf16 v[118:121], v[210:213], v[178:181], v[118:121]
	v_mfma_f32_16x16x32_bf16 v[114:117], v[218:221], v[178:181], v[114:117]
	v_mfma_f32_16x16x32_bf16 v[102:105], v[210:213], v[186:189], v[102:105]
	v_mfma_f32_16x16x32_bf16 v[98:101], v[218:221], v[186:189], v[98:101]
	v_mfma_f32_16x16x32_bf16 v[86:89], v[210:213], v[194:197], v[86:89]
	v_mfma_f32_16x16x32_bf16 v[82:85], v[218:221], v[194:197], v[82:85]
	v_mfma_f32_16x16x32_bf16 v[70:73], v[210:213], v[202:205], v[70:73]
	v_mfma_f32_16x16x32_bf16 v[66:69], v[218:221], v[202:205], v[66:69]
	s_barrier
	s_setprio 0
	s_add_i32 s18, s20, s42
	v_lshl_add_u64 v[174:175], v[174:175], 0, s[6:7]
	s_mov_b32 m0, s18
	s_nop 0
	global_load_lds_dwordx4 v[174:175], off
	v_lshl_add_u64 v[174:175], v[222:223], 0, s[6:7]
	s_add_i32 m0, s18, 0x2000
	s_nop 0
	global_load_lds_dwordx4 v[174:175], off
	s_mov_b32 m0, s50
	v_lshl_add_u64 v[174:175], v[224:225], 0, s[6:7]
	ds_read_b128 v[166:169], v173 offset:49152
	ds_read_b128 v[178:181], v173 offset:50176
	ds_read_b128 v[182:185], v173 offset:51200
	ds_read_b128 v[186:189], v173 offset:52224
	ds_read_b128 v[190:193], v173 offset:53248
	ds_read_b128 v[194:197], v173 offset:54272
	ds_read_b128 v[198:201], v173 offset:55296
	ds_read_b128 v[202:205], v173 offset:56320
	global_load_lds_dwordx4 v[174:175], off
	v_lshl_add_u64 v[174:175], v[226:227], 0, s[6:7]
	s_mov_b32 m0, s51
	s_nop 0
	global_load_lds_dwordx4 v[174:175], off
	s_add_u32 s18, s34, 0x40080
	s_addc_u32 s19, s35, 0
	s_add_i32 s20, s21, s42
	v_lshl_add_u64 v[252:253], s[18:19], 0, v[150:151]
	s_mov_b32 m0, s20
	s_nop 0
	global_load_lds_dwordx4 v[252:253], off
	v_lshl_add_u64 v[252:253], s[18:19], 0, v[146:147]
	s_add_i32 m0, s20, 0x2000
	s_nop 0
	global_load_lds_dwordx4 v[252:253], off
	s_waitcnt vmcnt(6)
	s_waitcnt lgkmcnt(0)
	s_setprio 1
	s_barrier
	v_mfma_f32_16x16x32_bf16 v[62:65], v[130:133], v[166:169], v[62:65]
	v_mfma_f32_16x16x32_bf16 v[58:61], v[138:141], v[166:169], v[58:61]
	v_mfma_f32_16x16x32_bf16 v[46:49], v[130:133], v[182:185], v[46:49]
	v_mfma_f32_16x16x32_bf16 v[42:45], v[138:141], v[182:185], v[42:45]
	v_mfma_f32_16x16x32_bf16 v[30:33], v[130:133], v[190:193], v[30:33]
	v_mfma_f32_16x16x32_bf16 v[26:29], v[138:141], v[190:193], v[26:29]
	v_mfma_f32_16x16x32_bf16 v[14:17], v[130:133], v[198:201], v[14:17]
	v_mfma_f32_16x16x32_bf16 v[10:13], v[138:141], v[198:201], v[10:13]
	v_mfma_f32_16x16x32_bf16 v[62:65], v[134:137], v[178:181], v[62:65]
	v_mfma_f32_16x16x32_bf16 v[58:61], v[142:145], v[178:181], v[58:61]
	v_mfma_f32_16x16x32_bf16 v[46:49], v[134:137], v[186:189], v[46:49]
	v_mfma_f32_16x16x32_bf16 v[42:45], v[142:145], v[186:189], v[42:45]
	v_mfma_f32_16x16x32_bf16 v[30:33], v[134:137], v[194:197], v[30:33]
	v_mfma_f32_16x16x32_bf16 v[26:29], v[142:145], v[194:197], v[26:29]
	v_mfma_f32_16x16x32_bf16 v[14:17], v[134:137], v[202:205], v[14:17]
	v_mfma_f32_16x16x32_bf16 v[10:13], v[142:145], v[202:205], v[10:13]
	v_mfma_f32_16x16x32_bf16 v[54:57], v[206:209], v[166:169], v[54:57]
	v_mfma_f32_16x16x32_bf16 v[50:53], v[214:217], v[166:169], v[50:53]
	v_mfma_f32_16x16x32_bf16 v[38:41], v[206:209], v[182:185], v[38:41]
	v_mfma_f32_16x16x32_bf16 v[34:37], v[214:217], v[182:185], v[34:37]
	v_mfma_f32_16x16x32_bf16 v[22:25], v[206:209], v[190:193], v[22:25]
	v_mfma_f32_16x16x32_bf16 v[18:21], v[214:217], v[190:193], v[18:21]
	v_mfma_f32_16x16x32_bf16 v[6:9], v[206:209], v[198:201], v[6:9]
	v_mfma_f32_16x16x32_bf16 v[2:5], v[214:217], v[198:201], v[2:5]
	v_mfma_f32_16x16x32_bf16 v[54:57], v[210:213], v[178:181], v[54:57]
	v_mfma_f32_16x16x32_bf16 v[50:53], v[218:221], v[178:181], v[50:53]
	v_mfma_f32_16x16x32_bf16 v[38:41], v[210:213], v[186:189], v[38:41]
	v_mfma_f32_16x16x32_bf16 v[34:37], v[218:221], v[186:189], v[34:37]
	v_mfma_f32_16x16x32_bf16 v[22:25], v[210:213], v[194:197], v[22:25]
	v_mfma_f32_16x16x32_bf16 v[18:21], v[218:221], v[194:197], v[18:21]
	v_mfma_f32_16x16x32_bf16 v[6:9], v[210:213], v[202:205], v[6:9]
	v_mfma_f32_16x16x32_bf16 v[2:5], v[218:221], v[202:205], v[2:5]
	s_add_i32 s63, s63, 2
	s_add_u32 s24, s24, 0x100
	s_addc_u32 s25, s25, 0
	s_add_u32 s61, s61, 0x100
	s_addc_u32 s62, s62, 0
	s_cmp_gt_u32 s63, 13

.Lp12_nopf:
	v_lshl_add_u64 v[174:175], s[24:25], 0, v[158:159]
	s_add_i32 m0, s43, 0xc000
	ds_read_b128 v[166:169], v173
	ds_read_b128 v[178:181], v173 offset:1024
	ds_read_b128 v[182:185], v173 offset:2048
	ds_read_b128 v[186:189], v173 offset:3072
	ds_read_b128 v[190:193], v173 offset:4096
	ds_read_b128 v[194:197], v173 offset:5120
	ds_read_b128 v[198:201], v173 offset:6144
	ds_read_b128 v[202:205], v173 offset:7168
	global_load_lds_dwordx4 v[174:175], off
	v_lshl_add_u64 v[174:175], s[24:25], 0, v[160:161]
	s_add_i32 m0, s43, 0xe000
	s_nop 0
	global_load_lds_dwordx4 v[174:175], off
	ds_read_b128 v[206:209], v177
	ds_read_b128 v[210:213], v177 offset:1024
	ds_read_b128 v[214:217], v177 offset:2048
	ds_read_b128 v[218:221], v177 offset:3072
	s_waitcnt lgkmcnt(0)
	s_setprio 1
	s_barrier
	v_mfma_f32_16x16x32_bf16 v[126:129], v[130:133], v[166:169], v[126:129]
	v_mfma_f32_16x16x32_bf16 v[122:125], v[138:141], v[166:169], v[122:125]
	v_mfma_f32_16x16x32_bf16 v[110:113], v[130:133], v[182:185], v[110:113]
	v_mfma_f32_16x16x32_bf16 v[106:109], v[138:141], v[182:185], v[106:109]
	v_mfma_f32_16x16x32_bf16 v[94:97], v[130:133], v[190:193], v[94:97]
	v_mfma_f32_16x16x32_bf16 v[90:93], v[138:141], v[190:193], v[90:93]
	v_mfma_f32_16x16x32_bf16 v[78:81], v[130:133], v[198:201], v[78:81]
	v_mfma_f32_16x16x32_bf16 v[74:77], v[138:141], v[198:201], v[74:77]
	v_mfma_f32_16x16x32_bf16 v[126:129], v[134:137], v[178:181], v[126:129]
	v_mfma_f32_16x16x32_bf16 v[122:125], v[142:145], v[178:181], v[122:125]
	v_mfma_f32_16x16x32_bf16 v[110:113], v[134:137], v[186:189], v[110:113]
	v_mfma_f32_16x16x32_bf16 v[106:109], v[142:145], v[186:189], v[106:109]
	v_mfma_f32_16x16x32_bf16 v[94:97], v[134:137], v[194:197], v[94:97]
	v_mfma_f32_16x16x32_bf16 v[90:93], v[142:145], v[194:197], v[90:93]
	v_mfma_f32_16x16x32_bf16 v[78:81], v[134:137], v[202:205], v[78:81]
	v_mfma_f32_16x16x32_bf16 v[74:77], v[142:145], v[202:205], v[74:77]
	v_mfma_f32_16x16x32_bf16 v[118:121], v[206:209], v[166:169], v[118:121]
	v_mfma_f32_16x16x32_bf16 v[114:117], v[214:217], v[166:169], v[114:117]
	v_mfma_f32_16x16x32_bf16 v[102:105], v[206:209], v[182:185], v[102:105]
	v_mfma_f32_16x16x32_bf16 v[98:101], v[214:217], v[182:185], v[98:101]
	v_mfma_f32_16x16x32_bf16 v[86:89], v[206:209], v[190:193], v[86:89]
	v_mfma_f32_16x16x32_bf16 v[82:85], v[214:217], v[190:193], v[82:85]
	v_mfma_f32_16x16x32_bf16 v[70:73], v[206:209], v[198:201], v[70:73]
	v_mfma_f32_16x16x32_bf16 v[66:69], v[214:217], v[198:201], v[66:69]
	v_mfma_f32_16x16x32_bf16 v[118:121], v[210:213], v[178:181], v[118:121]
	v_mfma_f32_16x16x32_bf16 v[114:117], v[218:221], v[178:181], v[114:117]
	v_mfma_f32_16x16x32_bf16 v[102:105], v[210:213], v[186:189], v[102:105]
	v_mfma_f32_16x16x32_bf16 v[98:101], v[218:221], v[186:189], v[98:101]
	v_mfma_f32_16x16x32_bf16 v[86:89], v[210:213], v[194:197], v[86:89]
	v_mfma_f32_16x16x32_bf16 v[82:85], v[218:221], v[194:197], v[82:85]
	v_mfma_f32_16x16x32_bf16 v[70:73], v[210:213], v[202:205], v[70:73]
	v_mfma_f32_16x16x32_bf16 v[66:69], v[218:221], v[202:205], v[66:69]
	s_barrier
	s_setprio 0
	s_add_i32 s20, s54, s42
	v_lshl_add_u64 v[174:175], s[34:35], 0, v[150:151]
	s_mov_b32 m0, s20
	s_nop 0
	global_load_lds_dwordx4 v[174:175], off
	v_lshl_add_u64 v[222:223], s[34:35], 0, v[146:147]
	s_add_i32 m0, s20, 0x2000
	s_nop 0
	global_load_lds_dwordx4 v[222:223], off
	s_mov_b32 m0, s43
	v_lshl_add_u64 v[224:225], s[18:19], 0, v[152:153]
	ds_read_b128 v[166:169], v173 offset:16384
	ds_read_b128 v[178:181], v173 offset:17408
	ds_read_b128 v[182:185], v173 offset:18432
	ds_read_b128 v[186:189], v173 offset:19456
	ds_read_b128 v[190:193], v173 offset:20480
	ds_read_b128 v[194:197], v173 offset:21504
	ds_read_b128 v[198:201], v173 offset:22528
	ds_read_b128 v[202:205], v173 offset:23552
	global_load_lds_dwordx4 v[224:225], off
	v_lshl_add_u64 v[226:227], s[18:19], 0, v[148:149]
	s_mov_b32 m0, s44
	s_nop 0
	global_load_lds_dwordx4 v[226:227], off
	s_cmp_eq_u32 s63, 12
	s_cbranch_scc1 .Lp12_q2last
	s_waitcnt vmcnt(6)
	s_branch .Lp12_q2join
.Lp12_q2last:
	s_waitcnt vmcnt(18)
.Lp12_q2join:
	s_waitcnt lgkmcnt(0)
	s_setprio 1
	s_barrier
	v_mfma_f32_16x16x32_bf16 v[62:65], v[130:133], v[166:169], v[62:65]
	v_mfma_f32_16x16x32_bf16 v[58:61], v[138:141], v[166:169], v[58:61]
	v_mfma_f32_16x16x32_bf16 v[46:49], v[130:133], v[182:185], v[46:49]
	v_mfma_f32_16x16x32_bf16 v[42:45], v[138:141], v[182:185], v[42:45]
	v_mfma_f32_16x16x32_bf16 v[30:33], v[130:133], v[190:193], v[30:33]
	v_mfma_f32_16x16x32_bf16 v[26:29], v[138:141], v[190:193], v[26:29]
	v_mfma_f32_16x16x32_bf16 v[14:17], v[130:133], v[198:201], v[14:17]
	v_mfma_f32_16x16x32_bf16 v[10:13], v[138:141], v[198:201], v[10:13]
	v_mfma_f32_16x16x32_bf16 v[62:65], v[134:137], v[178:181], v[62:65]
	v_mfma_f32_16x16x32_bf16 v[58:61], v[142:145], v[178:181], v[58:61]
	v_mfma_f32_16x16x32_bf16 v[46:49], v[134:137], v[186:189], v[46:49]
	v_mfma_f32_16x16x32_bf16 v[42:45], v[142:145], v[186:189], v[42:45]
	v_mfma_f32_16x16x32_bf16 v[30:33], v[134:137], v[194:197], v[30:33]
	v_mfma_f32_16x16x32_bf16 v[26:29], v[142:145], v[194:197], v[26:29]
	v_mfma_f32_16x16x32_bf16 v[14:17], v[134:137], v[202:205], v[14:17]
	v_mfma_f32_16x16x32_bf16 v[10:13], v[142:145], v[202:205], v[10:13]
	v_mfma_f32_16x16x32_bf16 v[54:57], v[206:209], v[166:169], v[54:57]
	v_mfma_f32_16x16x32_bf16 v[50:53], v[214:217], v[166:169], v[50:53]
	v_mfma_f32_16x16x32_bf16 v[38:41], v[206:209], v[182:185], v[38:41]
	v_mfma_f32_16x16x32_bf16 v[34:37], v[214:217], v[182:185], v[34:37]
	v_mfma_f32_16x16x32_bf16 v[22:25], v[206:209], v[190:193], v[22:25]
	v_mfma_f32_16x16x32_bf16 v[18:21], v[214:217], v[190:193], v[18:21]
	v_mfma_f32_16x16x32_bf16 v[6:9], v[206:209], v[198:201], v[6:9]
	v_mfma_f32_16x16x32_bf16 v[2:5], v[214:217], v[198:201], v[2:5]
	v_mfma_f32_16x16x32_bf16 v[54:57], v[210:213], v[178:181], v[54:57]
	v_mfma_f32_16x16x32_bf16 v[50:53], v[218:221], v[178:181], v[50:53]
	v_mfma_f32_16x16x32_bf16 v[38:41], v[210:213], v[186:189], v[38:41]
	v_mfma_f32_16x16x32_bf16 v[34:37], v[218:221], v[186:189], v[34:37]
	v_mfma_f32_16x16x32_bf16 v[22:25], v[210:213], v[194:197], v[22:25]
	v_mfma_f32_16x16x32_bf16 v[18:21], v[218:221], v[194:197], v[18:21]
	v_mfma_f32_16x16x32_bf16 v[6:9], v[210:213], v[202:205], v[6:9]
	v_mfma_f32_16x16x32_bf16 v[2:5], v[218:221], v[202:205], v[2:5]
	s_barrier
	s_setprio 0
	s_add_u32 s20, s34, 0x40000
	s_addc_u32 s21, s35, 0
	s_add_i32 s64, s55, s42
	v_lshl_add_u64 v[252:253], s[20:21], 0, v[150:151]
	s_mov_b32 m0, s64
	s_nop 0
	global_load_lds_dwordx4 v[252:253], off
	v_lshl_add_u64 v[252:253], s[20:21], 0, v[146:147]
	s_add_i32 m0, s64, 0x2000
	s_nop 0
	global_load_lds_dwordx4 v[252:253], off
	s_add_i32 s20, 0, 0x18000
	v_add_u32_e32 v142, s20, v157
	ds_read_b128 v[130:133], v142
	ds_read_b128 v[134:137], v142 offset:1024
	ds_read_b128 v[138:141], v142 offset:2048
	ds_read_b128 v[142:145], v142 offset:3072
	s_add_u32 s18, s18, 0x40000
	s_addc_u32 s19, s19, 0
	s_mov_b32 m0, s45
	v_lshl_add_u64 v[206:207], s[18:19], 0, v[152:153]
	ds_read_b128 v[166:169], v173 offset:32768
	ds_read_b128 v[178:181], v173 offset:33792
	ds_read_b128 v[182:185], v173 offset:34816
	ds_read_b128 v[186:189], v173 offset:35840
	ds_read_b128 v[190:193], v173 offset:36864
	ds_read_b128 v[194:197], v173 offset:37888
	ds_read_b128 v[198:201], v173 offset:38912
	ds_read_b128 v[202:205], v173 offset:39936
	global_load_lds_dwordx4 v[206:207], off
	v_lshl_add_u64 v[206:207], s[18:19], 0, v[148:149]
	s_mov_b32 m0, s46
	s_nop 0
	global_load_lds_dwordx4 v[206:207], off
	s_add_i32 s21, 0, 0x1c000
	v_add_u32_e32 v154, s21, v157
	ds_read_b128 v[206:209], v154
	ds_read_b128 v[210:213], v154 offset:1024
	ds_read_b128 v[214:217], v154 offset:2048
	ds_read_b128 v[218:221], v154 offset:3072
	s_waitcnt vmcnt(8)
	s_waitcnt lgkmcnt(0)
	s_setprio 1
	s_barrier
	v_mfma_f32_16x16x32_bf16 v[126:129], v[130:133], v[166:169], v[126:129]
	v_mfma_f32_16x16x32_bf16 v[122:125], v[138:141], v[166:169], v[122:125]
	v_mfma_f32_16x16x32_bf16 v[110:113], v[130:133], v[182:185], v[110:113]
	v_mfma_f32_16x16x32_bf16 v[106:109], v[138:141], v[182:185], v[106:109]
	v_mfma_f32_16x16x32_bf16 v[94:97], v[130:133], v[190:193], v[94:97]
	v_mfma_f32_16x16x32_bf16 v[90:93], v[138:141], v[190:193], v[90:93]
	v_mfma_f32_16x16x32_bf16 v[78:81], v[130:133], v[198:201], v[78:81]
	v_mfma_f32_16x16x32_bf16 v[74:77], v[138:141], v[198:201], v[74:77]
	v_mfma_f32_16x16x32_bf16 v[126:129], v[134:137], v[178:181], v[126:129]
	v_mfma_f32_16x16x32_bf16 v[122:125], v[142:145], v[178:181], v[122:125]
	v_mfma_f32_16x16x32_bf16 v[110:113], v[134:137], v[186:189], v[110:113]
	v_mfma_f32_16x16x32_bf16 v[106:109], v[142:145], v[186:189], v[106:109]
	v_mfma_f32_16x16x32_bf16 v[94:97], v[134:137], v[194:197], v[94:97]
	v_mfma_f32_16x16x32_bf16 v[90:93], v[142:145], v[194:197], v[90:93]
	v_mfma_f32_16x16x32_bf16 v[78:81], v[134:137], v[202:205], v[78:81]
	v_mfma_f32_16x16x32_bf16 v[74:77], v[142:145], v[202:205], v[74:77]
	v_mfma_f32_16x16x32_bf16 v[118:121], v[206:209], v[166:169], v[118:121]
	v_mfma_f32_16x16x32_bf16 v[114:117], v[214:217], v[166:169], v[114:117]
	v_mfma_f32_16x16x32_bf16 v[102:105], v[206:209], v[182:185], v[102:105]
	v_mfma_f32_16x16x32_bf16 v[98:101], v[214:217], v[182:185], v[98:101]
	v_mfma_f32_16x16x32_bf16 v[86:89], v[206:209], v[190:193], v[86:89]
	v_mfma_f32_16x16x32_bf16 v[82:85], v[214:217], v[190:193], v[82:85]
	v_mfma_f32_16x16x32_bf16 v[70:73], v[206:209], v[198:201], v[70:73]
	v_mfma_f32_16x16x32_bf16 v[66:69], v[214:217], v[198:201], v[66:69]
	v_mfma_f32_16x16x32_bf16 v[118:121], v[210:213], v[178:181], v[118:121]
	v_mfma_f32_16x16x32_bf16 v[114:117], v[218:221], v[178:181], v[114:117]
	v_mfma_f32_16x16x32_bf16 v[102:105], v[210:213], v[186:189], v[102:105]
	v_mfma_f32_16x16x32_bf16 v[98:101], v[218:221], v[186:189], v[98:101]
	v_mfma_f32_16x16x32_bf16 v[86:89], v[210:213], v[194:197], v[86:89]
	v_mfma_f32_16x16x32_bf16 v[82:85], v[218:221], v[194:197], v[82:85]
	v_mfma_f32_16x16x32_bf16 v[70:73], v[210:213], v[202:205], v[70:73]
	v_mfma_f32_16x16x32_bf16 v[66:69], v[218:221], v[202:205], v[66:69]
	s_barrier
	s_setprio 0
	s_add_i32 s18, s20, s42
	v_lshl_add_u64 v[174:175], v[174:175], 0, s[6:7]
	s_mov_b32 m0, s18
	s_nop 0
	global_load_lds_dwordx4 v[174:175], off
	v_lshl_add_u64 v[174:175], v[222:223], 0, s[6:7]
	s_add_i32 m0, s18, 0x2000
	s_nop 0
	global_load_lds_dwordx4 v[174:175], off
	s_mov_b32 m0, s50
	v_lshl_add_u64 v[174:175], v[224:225], 0, s[6:7]
	ds_read_b128 v[166:169], v173 offset:49152
	ds_read_b128 v[178:181], v173 offset:50176
	ds_read_b128 v[182:185], v173 offset:51200
	ds_read_b128 v[186:189], v173 offset:52224
	ds_read_b128 v[190:193], v173 offset:53248
	ds_read_b128 v[194:197], v173 offset:54272
	ds_read_b128 v[198:201], v173 offset:55296
	ds_read_b128 v[202:205], v173 offset:56320
	global_load_lds_dwordx4 v[174:175], off
	v_lshl_add_u64 v[174:175], v[226:227], 0, s[6:7]
	s_mov_b32 m0, s51
	s_nop 0
	global_load_lds_dwordx4 v[174:175], off
	s_add_u32 s18, s34, 0x40080
	s_addc_u32 s19, s35, 0
	s_add_i32 s20, s21, s42
	v_lshl_add_u64 v[252:253], s[18:19], 0, v[150:151]
	s_mov_b32 m0, s20
	s_nop 0
	global_load_lds_dwordx4 v[252:253], off
	v_lshl_add_u64 v[252:253], s[18:19], 0, v[146:147]
	s_add_i32 m0, s20, 0x2000
	s_nop 0
	global_load_lds_dwordx4 v[252:253], off
	s_waitcnt vmcnt(6)
	s_waitcnt lgkmcnt(0)
	s_setprio 1
	s_barrier
	v_mfma_f32_16x16x32_bf16 v[62:65], v[130:133], v[166:169], v[62:65]
	v_mfma_f32_16x16x32_bf16 v[58:61], v[138:141], v[166:169], v[58:61]
	v_mfma_f32_16x16x32_bf16 v[46:49], v[130:133], v[182:185], v[46:49]
	v_mfma_f32_16x16x32_bf16 v[42:45], v[138:141], v[182:185], v[42:45]
	v_mfma_f32_16x16x32_bf16 v[30:33], v[130:133], v[190:193], v[30:33]
	v_mfma_f32_16x16x32_bf16 v[26:29], v[138:141], v[190:193], v[26:29]
	v_mfma_f32_16x16x32_bf16 v[14:17], v[130:133], v[198:201], v[14:17]
	v_mfma_f32_16x16x32_bf16 v[10:13], v[138:141], v[198:201], v[10:13]
	v_mfma_f32_16x16x32_bf16 v[62:65], v[134:137], v[178:181], v[62:65]
	v_mfma_f32_16x16x32_bf16 v[58:61], v[142:145], v[178:181], v[58:61]
	v_mfma_f32_16x16x32_bf16 v[46:49], v[134:137], v[186:189], v[46:49]
	v_mfma_f32_16x16x32_bf16 v[42:45], v[142:145], v[186:189], v[42:45]
	v_mfma_f32_16x16x32_bf16 v[30:33], v[134:137], v[194:197], v[30:33]
	v_mfma_f32_16x16x32_bf16 v[26:29], v[142:145], v[194:197], v[26:29]
	v_mfma_f32_16x16x32_bf16 v[14:17], v[134:137], v[202:205], v[14:17]
	v_mfma_f32_16x16x32_bf16 v[10:13], v[142:145], v[202:205], v[10:13]
	v_mfma_f32_16x16x32_bf16 v[54:57], v[206:209], v[166:169], v[54:57]
	v_mfma_f32_16x16x32_bf16 v[50:53], v[214:217], v[166:169], v[50:53]
	v_mfma_f32_16x16x32_bf16 v[38:41], v[206:209], v[182:185], v[38:41]
	v_mfma_f32_16x16x32_bf16 v[34:37], v[214:217], v[182:185], v[34:37]
	v_mfma_f32_16x16x32_bf16 v[22:25], v[206:209], v[190:193], v[22:25]
	v_mfma_f32_16x16x32_bf16 v[18:21], v[214:217], v[190:193], v[18:21]
	v_mfma_f32_16x16x32_bf16 v[6:9], v[206:209], v[198:201], v[6:9]
	v_mfma_f32_16x16x32_bf16 v[2:5], v[214:217], v[198:201], v[2:5]
	v_mfma_f32_16x16x32_bf16 v[54:57], v[210:213], v[178:181], v[54:57]
	v_mfma_f32_16x16x32_bf16 v[50:53], v[218:221], v[178:181], v[50:53]
	v_mfma_f32_16x16x32_bf16 v[38:41], v[210:213], v[186:189], v[38:41]
	v_mfma_f32_16x16x32_bf16 v[34:37], v[218:221], v[186:189], v[34:37]
	v_mfma_f32_16x16x32_bf16 v[22:25], v[210:213], v[194:197], v[22:25]
	v_mfma_f32_16x16x32_bf16 v[18:21], v[218:221], v[194:197], v[18:21]
	v_mfma_f32_16x16x32_bf16 v[6:9], v[210:213], v[202:205], v[6:9]
	v_mfma_f32_16x16x32_bf16 v[2:5], v[218:221], v[202:205], v[2:5]
	s_add_i32 s63, s63, 2
	s_add_u32 s24, s24, 0x100
	s_addc_u32 s25, s25, 0
	s_add_u32 s61, s61, 0x100
	s_addc_u32 s62, s62, 0
	s_cmp_gt_u32 s63, 13
	s_cbranch_scc0 .Ldfr_p12_r
	s_cmpk_gt_u32 s33, 0xff
	s_cbranch_scc1 .Ldfr_p12_b
	s_barrier
.Ldfr_p12_b:
	s_mov_b32 s20, 0xbfb8aa3b
	s_setprio 0
	s_ashr_i32 s9, s16, 3
	s_mul_hi_i32 s11, s9, 0x5800
	s_mulk_i32 s9, 0x5800
	s_add_u32 s9, s48, s9
	s_addc_u32 s11, s49, s11
	s_lshl_b32 s18, s17, 8
	s_ashr_i32 s19, s18, 31
	s_lshl_b64 s[18:19], s[18:19], 2
	v_lshl_add_u32 v180, s16, 8, v1
	s_add_u32 s18, s9, s18
	s_addc_u32 s19, s11, s19
	v_lshlrev_b32_e32 v130, 2, v156
	v_ashrrev_i32_e32 v181, 31, v180
	v_mov_b32_e32 v142, v236
	v_mov_b32_e32 v143, v237
	v_mov_b32_e32 v144, v238
	v_mov_b32_e32 v145, v239
	v_lshl_add_u64 v[182:183], v[180:181], 2, s[4:5]
	v_mov_b32_e32 v190, v228
	v_mov_b32_e32 v138, v240
	v_mov_b32_e32 v139, v241
	v_mov_b32_e32 v140, v242
	v_mov_b32_e32 v141, v243
	v_mov_b32_e32 v134, v244
	v_mov_b32_e32 v135, v245
	v_mov_b32_e32 v136, v246
	v_mov_b32_e32 v137, v247
	s_nop 0
	v_mov_b32_e32 v130, v248
	v_mov_b32_e32 v131, v249
	v_mov_b32_e32 v132, v250
	v_mov_b32_e32 v133, v251
	v_or_b32_e32 v192, 16, v180
	v_ashrrev_i32_e32 v193, 31, v192
	v_lshl_add_u64 v[168:169], v[192:193], 2, s[4:5]
	v_mov_b32_e32 v194, v229
	v_or_b32_e32 v188, 32, v180
	v_or_b32_e32 v184, 48, v180
	v_mov_b64_e32 v[166:167], s[0:1]
	v_add_u32_e32 v178, 0x90, v180
	v_add_u32_e32 v174, 0xa0, v180
	v_add_u32_e32 v168, 0xb0, v180
	v_ashrrev_i32_e32 v189, 31, v188
	v_ashrrev_i32_e32 v185, 31, v184
	v_add_u32_e32 v193, 0x80, v180
	v_mad_i64_i32 v[196:197], s[18:19], v180, s56, v[166:167]
	v_ashrrev_i32_e32 v179, 31, v178
	v_ashrrev_i32_e32 v175, 31, v174
	v_ashrrev_i32_e32 v169, 31, v168
	v_lshl_add_u64 v[180:181], v[188:189], 2, s[4:5]
	v_lshl_add_u64 v[186:187], v[184:185], 2, s[4:5]
	v_lshl_add_u64 v[198:199], v[178:179], 2, s[4:5]
	v_lshl_add_u64 v[200:201], v[174:175], 2, s[4:5]
	v_lshl_add_u64 v[202:203], v[168:169], 2, s[4:5]
	v_mov_b32_e32 v204, v233
	s_nop 0
	v_mov_b32_e32 v186, v234
	s_nop 0
	v_mov_b32_e32 v180, v255
	s_nop 0
	v_mov_b32_e32 v182, v235
	s_lshl_b32 s16, s17, 7
	s_ashr_i32 s17, s16, 31
	s_lshl_b64 s[16:17], s[16:17], 1
	v_lshlrev_b32_e32 v154, 1, v156
	v_lshl_add_u64 v[196:197], v[196:197], 0, s[16:17]
	s_and_b64 vcc, exec, s[2:3]
	s_mov_b64 s[34:35], s[14:15]
	s_mov_b64 s[24:25], s[12:13]
	v_pk_fma_f32 v[118:119], v[118:119], v[190:191], v[138:139] op_sel_hi:[1,0,1]
	v_pk_fma_f32 v[126:127], v[126:127], v[190:191], v[142:143] op_sel_hi:[1,0,1]
	v_pk_fma_f32 v[128:129], v[128:129], v[190:191], v[144:145] op_sel_hi:[1,0,1]
	v_pk_fma_f32 v[122:123], v[122:123], v[190:191], v[134:135] op_sel_hi:[1,0,1]
	v_pk_fma_f32 v[124:125], v[124:125], v[190:191], v[136:137] op_sel_hi:[1,0,1]
	v_mul_f32_e32 v169, 0xbfb8aa3b, v126
	v_mul_f32_e32 v175, 0xbfb8aa3b, v127
	v_mul_f32_e32 v179, 0xbfb8aa3b, v128
	v_mul_f32_e32 v181, 0xbfb8aa3b, v129
	v_mul_f32_e32 v183, 0xbfb8aa3b, v122
	v_mul_f32_e32 v185, 0xbfb8aa3b, v123
	v_mul_f32_e32 v187, 0xbfb8aa3b, v124
	v_mul_f32_e32 v189, 0xbfb8aa3b, v125
	v_exp_f32_e32 v169, v169
	v_exp_f32_e32 v175, v175
	v_exp_f32_e32 v179, v179
	v_exp_f32_e32 v181, v181
	v_exp_f32_e32 v183, v183
	v_exp_f32_e32 v185, v185
	v_exp_f32_e32 v187, v187
	v_exp_f32_e32 v189, v189
	v_add_f32_e32 v169, 1.0, v169
	v_add_f32_e32 v175, 1.0, v175
	v_add_f32_e32 v179, 1.0, v179
	v_add_f32_e32 v181, 1.0, v181
	v_add_f32_e32 v183, 1.0, v183
	v_add_f32_e32 v185, 1.0, v185
	v_add_f32_e32 v187, 1.0, v187
	v_add_f32_e32 v189, 1.0, v189
	v_pk_fma_f32 v[120:121], v[120:121], v[190:191], v[140:141] op_sel_hi:[1,0,1]
	v_pk_fma_f32 v[114:115], v[114:115], v[190:191], v[130:131] op_sel_hi:[1,0,1]
	v_pk_fma_f32 v[116:117], v[116:117], v[190:191], v[132:133] op_sel_hi:[1,0,1]
	v_rcp_f32_e32 v190, v169
	v_rcp_f32_e32 v191, v175
	v_rcp_f32_e32 v198, v179
	v_rcp_f32_e32 v199, v181
	v_rcp_f32_e32 v200, v183
	v_rcp_f32_e32 v201, v185
	v_rcp_f32_e32 v202, v187
	v_rcp_f32_e32 v203, v189
	v_pk_mul_f32 v[126:127], v[126:127], v[190:191]
	v_pk_mul_f32 v[128:129], v[128:129], v[198:199]
	v_pk_mul_f32 v[122:123], v[122:123], v[200:201]
	v_pk_mul_f32 v[124:125], v[124:125], v[202:203]
	v_pk_mul_f32 v[118:119], v[118:119], v[126:127]
	v_pk_mul_f32 v[120:121], v[120:121], v[128:129]
	v_pk_mul_f32 v[122:123], v[114:115], v[122:123]
	v_pk_mul_f32 v[124:125], v[116:117], v[124:125]
	v_pk_fma_f32 v[110:111], v[110:111], v[194:195], v[142:143] op_sel_hi:[1,0,1]
	v_lshl_add_u64 v[126:127], v[196:197], 0, v[154:155]
	v_cvt_pk_bf16_f32 v114, v118, v119
	v_cvt_pk_bf16_f32 v115, v120, v121
	v_cvt_pk_bf16_f32 v116, v122, v123
	v_cvt_pk_bf16_f32 v117, v124, v125
	v_pk_mul_f32 v[118:119], v[110:111], s[20:21] op_sel_hi:[1,0]
	v_pk_fma_f32 v[112:113], v[112:113], v[194:195], v[144:145] op_sel_hi:[1,0,1]
	v_exp_f32_e32 v118, v118
	v_exp_f32_e32 v119, v119
	global_store_dwordx4 v[126:127], v[114:117], off nt
	v_pk_fma_f32 v[102:103], v[102:103], v[194:195], v[138:139] op_sel_hi:[1,0,1]
	v_pk_fma_f32 v[106:107], v[106:107], v[194:195], v[134:135] op_sel_hi:[1,0,1]
	v_pk_mul_f32 v[116:117], v[112:113], s[20:21] op_sel_hi:[1,0]
	v_exp_f32_e32 v116, v116
	v_exp_f32_e32 v117, v117
	v_pk_add_f32 v[114:115], v[118:119], 1.0 op_sel_hi:[1,0]
	v_rcp_f32_e32 v114, v114
	v_rcp_f32_e32 v115, v115
	v_pk_add_f32 v[116:117], v[116:117], 1.0 op_sel_hi:[1,0]
	v_rcp_f32_e32 v116, v116
	v_rcp_f32_e32 v117, v117
	v_pk_mul_f32 v[110:111], v[110:111], v[114:115]
	v_pk_fma_f32 v[104:105], v[104:105], v[194:195], v[140:141] op_sel_hi:[1,0,1]
	v_pk_mul_f32 v[102:103], v[102:103], v[110:111]
	v_pk_mul_f32 v[110:111], v[112:113], v[116:117]
	v_pk_mul_f32 v[112:113], v[106:107], s[20:21] op_sel_hi:[1,0]
	v_exp_f32_e32 v112, v112
	v_exp_f32_e32 v113, v113
	v_pk_fma_f32 v[108:109], v[108:109], v[194:195], v[136:137] op_sel_hi:[1,0,1]
	v_pk_mul_f32 v[104:105], v[104:105], v[110:111]
	v_pk_add_f32 v[110:111], v[112:113], 1.0 op_sel_hi:[1,0]
	v_pk_mul_f32 v[112:113], v[108:109], s[20:21] op_sel_hi:[1,0]
	v_exp_f32_e32 v112, v112
	v_exp_f32_e32 v113, v113
	v_rcp_f32_e32 v110, v110
	v_rcp_f32_e32 v111, v111
	v_pk_add_f32 v[112:113], v[112:113], 1.0 op_sel_hi:[1,0]
	v_rcp_f32_e32 v112, v112
	v_rcp_f32_e32 v113, v113
	v_pk_mul_f32 v[106:107], v[106:107], v[110:111]
	v_pk_fma_f32 v[98:99], v[98:99], v[194:195], v[130:131] op_sel_hi:[1,0,1]
	v_pk_fma_f32 v[100:101], v[100:101], v[194:195], v[132:133] op_sel_hi:[1,0,1]
	v_pk_mul_f32 v[106:107], v[98:99], v[106:107]
	v_pk_mul_f32 v[98:99], v[108:109], v[112:113]
	v_pk_fma_f32 v[94:95], v[94:95], v[204:205], v[142:143] op_sel_hi:[1,0,1]
	v_pk_mul_f32 v[108:109], v[100:101], v[98:99]
	v_mad_i64_i32 v[98:99], s[18:19], v192, s56, v[166:167]
	v_lshl_add_u64 v[98:99], v[98:99], 0, s[16:17]
	v_lshl_add_u64 v[110:111], v[98:99], 0, v[154:155]
	v_cvt_pk_bf16_f32 v98, v102, v103
	v_cvt_pk_bf16_f32 v99, v104, v105
	v_cvt_pk_bf16_f32 v100, v106, v107
	v_cvt_pk_bf16_f32 v101, v108, v109
	v_pk_mul_f32 v[102:103], v[94:95], s[20:21] op_sel_hi:[1,0]
	v_pk_fma_f32 v[96:97], v[96:97], v[204:205], v[144:145] op_sel_hi:[1,0,1]
	v_exp_f32_e32 v102, v102
	v_exp_f32_e32 v103, v103
	global_store_dwordx4 v[110:111], v[98:101], off nt
	v_pk_fma_f32 v[86:87], v[86:87], v[204:205], v[138:139] op_sel_hi:[1,0,1]
	v_pk_fma_f32 v[90:91], v[90:91], v[204:205], v[134:135] op_sel_hi:[1,0,1]
	v_pk_mul_f32 v[100:101], v[96:97], s[20:21] op_sel_hi:[1,0]
	v_exp_f32_e32 v100, v100
	v_exp_f32_e32 v101, v101
	v_pk_add_f32 v[98:99], v[102:103], 1.0 op_sel_hi:[1,0]
	v_rcp_f32_e32 v98, v98
	v_rcp_f32_e32 v99, v99
	v_pk_add_f32 v[100:101], v[100:101], 1.0 op_sel_hi:[1,0]
	v_rcp_f32_e32 v100, v100
	v_rcp_f32_e32 v101, v101
	v_pk_mul_f32 v[94:95], v[94:95], v[98:99]
	v_pk_fma_f32 v[88:89], v[88:89], v[204:205], v[140:141] op_sel_hi:[1,0,1]
	v_pk_mul_f32 v[86:87], v[86:87], v[94:95]
	v_pk_mul_f32 v[94:95], v[96:97], v[100:101]
	v_pk_mul_f32 v[96:97], v[90:91], s[20:21] op_sel_hi:[1,0]
	v_exp_f32_e32 v96, v96
	v_exp_f32_e32 v97, v97
	v_pk_fma_f32 v[92:93], v[92:93], v[204:205], v[136:137] op_sel_hi:[1,0,1]
	v_pk_mul_f32 v[88:89], v[88:89], v[94:95]
	v_pk_add_f32 v[94:95], v[96:97], 1.0 op_sel_hi:[1,0]
	v_pk_mul_f32 v[96:97], v[92:93], s[20:21] op_sel_hi:[1,0]
	v_exp_f32_e32 v96, v96
	v_exp_f32_e32 v97, v97
	v_rcp_f32_e32 v94, v94
	v_rcp_f32_e32 v95, v95
	v_pk_add_f32 v[96:97], v[96:97], 1.0 op_sel_hi:[1,0]
	v_rcp_f32_e32 v96, v96
	v_rcp_f32_e32 v97, v97
	v_pk_mul_f32 v[90:91], v[90:91], v[94:95]
	v_pk_fma_f32 v[82:83], v[82:83], v[204:205], v[130:131] op_sel_hi:[1,0,1]
	v_pk_fma_f32 v[84:85], v[84:85], v[204:205], v[132:133] op_sel_hi:[1,0,1]
	v_pk_mul_f32 v[90:91], v[82:83], v[90:91]
	v_pk_mul_f32 v[82:83], v[92:93], v[96:97]
	v_pk_fma_f32 v[78:79], v[78:79], v[186:187], v[142:143] op_sel_hi:[1,0,1]
	v_pk_mul_f32 v[92:93], v[84:85], v[82:83]
	v_mad_i64_i32 v[82:83], s[18:19], v188, s56, v[166:167]
	v_lshl_add_u64 v[82:83], v[82:83], 0, s[16:17]
	v_lshl_add_u64 v[94:95], v[82:83], 0, v[154:155]
	v_cvt_pk_bf16_f32 v82, v86, v87
	v_cvt_pk_bf16_f32 v83, v88, v89
	v_cvt_pk_bf16_f32 v84, v90, v91
	v_cvt_pk_bf16_f32 v85, v92, v93
	v_pk_mul_f32 v[86:87], v[78:79], s[20:21] op_sel_hi:[1,0]
	v_pk_fma_f32 v[80:81], v[80:81], v[186:187], v[144:145] op_sel_hi:[1,0,1]
	v_exp_f32_e32 v86, v86
	v_exp_f32_e32 v87, v87
	global_store_dwordx4 v[94:95], v[82:85], off nt
	v_pk_fma_f32 v[70:71], v[70:71], v[186:187], v[138:139] op_sel_hi:[1,0,1]
	v_pk_fma_f32 v[74:75], v[74:75], v[186:187], v[134:135] op_sel_hi:[1,0,1]
	v_pk_mul_f32 v[84:85], v[80:81], s[20:21] op_sel_hi:[1,0]
	v_exp_f32_e32 v84, v84
	v_exp_f32_e32 v85, v85
	v_pk_add_f32 v[82:83], v[86:87], 1.0 op_sel_hi:[1,0]
	v_rcp_f32_e32 v82, v82
	v_rcp_f32_e32 v83, v83
	v_pk_add_f32 v[84:85], v[84:85], 1.0 op_sel_hi:[1,0]
	v_rcp_f32_e32 v84, v84
	v_rcp_f32_e32 v85, v85
	v_pk_mul_f32 v[78:79], v[78:79], v[82:83]
	v_pk_fma_f32 v[72:73], v[72:73], v[186:187], v[140:141] op_sel_hi:[1,0,1]
	v_pk_mul_f32 v[70:71], v[70:71], v[78:79]
	v_pk_mul_f32 v[78:79], v[80:81], v[84:85]
	v_pk_mul_f32 v[80:81], v[74:75], s[20:21] op_sel_hi:[1,0]
	v_exp_f32_e32 v80, v80
	v_exp_f32_e32 v81, v81
	v_pk_fma_f32 v[76:77], v[76:77], v[186:187], v[136:137] op_sel_hi:[1,0,1]
	v_pk_mul_f32 v[72:73], v[72:73], v[78:79]
	v_pk_add_f32 v[78:79], v[80:81], 1.0 op_sel_hi:[1,0]
	v_pk_mul_f32 v[80:81], v[76:77], s[20:21] op_sel_hi:[1,0]
	v_exp_f32_e32 v80, v80
	v_exp_f32_e32 v81, v81
	v_rcp_f32_e32 v78, v78
	v_rcp_f32_e32 v79, v79
	v_pk_add_f32 v[80:81], v[80:81], 1.0 op_sel_hi:[1,0]
	v_rcp_f32_e32 v80, v80
	v_rcp_f32_e32 v81, v81
	v_pk_mul_f32 v[74:75], v[74:75], v[78:79]
	v_pk_fma_f32 v[66:67], v[66:67], v[186:187], v[130:131] op_sel_hi:[1,0,1]
	v_pk_fma_f32 v[68:69], v[68:69], v[186:187], v[132:133] op_sel_hi:[1,0,1]
	v_pk_mul_f32 v[74:75], v[66:67], v[74:75]
	v_pk_mul_f32 v[66:67], v[76:77], v[80:81]
	v_pk_fma_f32 v[62:63], v[62:63], v[182:183], v[142:143] op_sel_hi:[1,0,1]
	v_pk_mul_f32 v[76:77], v[68:69], v[66:67]
	v_mad_i64_i32 v[66:67], s[18:19], v184, s56, v[166:167]
	v_lshl_add_u64 v[66:67], v[66:67], 0, s[16:17]
	v_lshl_add_u64 v[78:79], v[66:67], 0, v[154:155]
	v_cvt_pk_bf16_f32 v66, v70, v71
	v_cvt_pk_bf16_f32 v67, v72, v73
	v_cvt_pk_bf16_f32 v68, v74, v75
	v_cvt_pk_bf16_f32 v69, v76, v77
	v_pk_mul_f32 v[70:71], v[62:63], s[20:21] op_sel_hi:[1,0]
	v_pk_fma_f32 v[64:65], v[64:65], v[182:183], v[144:145] op_sel_hi:[1,0,1]
	v_exp_f32_e32 v70, v70
	v_exp_f32_e32 v71, v71
	global_store_dwordx4 v[78:79], v[66:69], off nt
	v_pk_fma_f32 v[54:55], v[54:55], v[182:183], v[138:139] op_sel_hi:[1,0,1]
	v_pk_fma_f32 v[58:59], v[58:59], v[182:183], v[134:135] op_sel_hi:[1,0,1]
	v_pk_mul_f32 v[68:69], v[64:65], s[20:21] op_sel_hi:[1,0]
	v_exp_f32_e32 v68, v68
	v_exp_f32_e32 v69, v69
	v_pk_add_f32 v[66:67], v[70:71], 1.0 op_sel_hi:[1,0]
	v_rcp_f32_e32 v66, v66
	v_rcp_f32_e32 v67, v67
	v_pk_add_f32 v[68:69], v[68:69], 1.0 op_sel_hi:[1,0]
	v_rcp_f32_e32 v68, v68
	v_rcp_f32_e32 v69, v69
	v_pk_mul_f32 v[62:63], v[62:63], v[66:67]
	v_pk_fma_f32 v[56:57], v[56:57], v[182:183], v[140:141] op_sel_hi:[1,0,1]
	v_pk_mul_f32 v[54:55], v[54:55], v[62:63]
	v_pk_mul_f32 v[62:63], v[64:65], v[68:69]
	v_pk_mul_f32 v[64:65], v[58:59], s[20:21] op_sel_hi:[1,0]
	v_exp_f32_e32 v64, v64
	v_exp_f32_e32 v65, v65
	v_pk_fma_f32 v[60:61], v[60:61], v[182:183], v[136:137] op_sel_hi:[1,0,1]
	v_pk_mul_f32 v[56:57], v[56:57], v[62:63]
	v_pk_add_f32 v[62:63], v[64:65], 1.0 op_sel_hi:[1,0]
	v_pk_mul_f32 v[64:65], v[60:61], s[20:21] op_sel_hi:[1,0]
	v_exp_f32_e32 v64, v64
	v_exp_f32_e32 v65, v65
	v_rcp_f32_e32 v62, v62
	v_rcp_f32_e32 v63, v63
	v_pk_add_f32 v[64:65], v[64:65], 1.0 op_sel_hi:[1,0]
	v_rcp_f32_e32 v64, v64
	v_rcp_f32_e32 v65, v65
	v_pk_mul_f32 v[58:59], v[58:59], v[62:63]
	v_pk_fma_f32 v[50:51], v[50:51], v[182:183], v[130:131] op_sel_hi:[1,0,1]
	v_pk_fma_f32 v[52:53], v[52:53], v[182:183], v[132:133] op_sel_hi:[1,0,1]
	v_pk_mul_f32 v[58:59], v[50:51], v[58:59]
	v_pk_mul_f32 v[50:51], v[60:61], v[64:65]
	v_pk_fma_f32 v[46:47], v[46:47], v[180:181], v[142:143] op_sel_hi:[1,0,1]
	v_pk_mul_f32 v[60:61], v[52:53], v[50:51]
	v_mad_i64_i32 v[50:51], s[18:19], v193, s56, v[166:167]
	v_lshl_add_u64 v[50:51], v[50:51], 0, s[16:17]
	v_lshl_add_u64 v[62:63], v[50:51], 0, v[154:155]
	v_cvt_pk_bf16_f32 v50, v54, v55
	v_cvt_pk_bf16_f32 v51, v56, v57
	v_cvt_pk_bf16_f32 v52, v58, v59
	v_cvt_pk_bf16_f32 v53, v60, v61
	v_pk_mul_f32 v[54:55], v[46:47], s[20:21] op_sel_hi:[1,0]
	v_pk_fma_f32 v[48:49], v[48:49], v[180:181], v[144:145] op_sel_hi:[1,0,1]
	v_exp_f32_e32 v54, v54
	v_exp_f32_e32 v55, v55
	global_store_dwordx4 v[62:63], v[50:53], off nt
	v_pk_fma_f32 v[38:39], v[38:39], v[180:181], v[138:139] op_sel_hi:[1,0,1]
	v_pk_fma_f32 v[42:43], v[42:43], v[180:181], v[134:135] op_sel_hi:[1,0,1]
	v_pk_mul_f32 v[52:53], v[48:49], s[20:21] op_sel_hi:[1,0]
	v_exp_f32_e32 v52, v52
	v_exp_f32_e32 v53, v53
	v_pk_add_f32 v[50:51], v[54:55], 1.0 op_sel_hi:[1,0]
	v_rcp_f32_e32 v50, v50
	v_rcp_f32_e32 v51, v51
	v_pk_add_f32 v[52:53], v[52:53], 1.0 op_sel_hi:[1,0]
	v_rcp_f32_e32 v52, v52
	v_rcp_f32_e32 v53, v53
	v_pk_mul_f32 v[46:47], v[46:47], v[50:51]
	v_pk_fma_f32 v[40:41], v[40:41], v[180:181], v[140:141] op_sel_hi:[1,0,1]
	v_pk_mul_f32 v[38:39], v[38:39], v[46:47]
	v_pk_mul_f32 v[46:47], v[48:49], v[52:53]
	v_pk_mul_f32 v[48:49], v[42:43], s[20:21] op_sel_hi:[1,0]
	v_exp_f32_e32 v48, v48
	v_exp_f32_e32 v49, v49
	v_pk_fma_f32 v[44:45], v[44:45], v[180:181], v[136:137] op_sel_hi:[1,0,1]
	v_pk_mul_f32 v[40:41], v[40:41], v[46:47]
	v_pk_add_f32 v[46:47], v[48:49], 1.0 op_sel_hi:[1,0]
	v_pk_mul_f32 v[48:49], v[44:45], s[20:21] op_sel_hi:[1,0]
	v_exp_f32_e32 v48, v48
	v_exp_f32_e32 v49, v49
	v_rcp_f32_e32 v46, v46
	v_rcp_f32_e32 v47, v47
	v_pk_add_f32 v[48:49], v[48:49], 1.0 op_sel_hi:[1,0]
	v_rcp_f32_e32 v48, v48
	v_rcp_f32_e32 v49, v49
	v_pk_mul_f32 v[42:43], v[42:43], v[46:47]
	v_pk_fma_f32 v[34:35], v[34:35], v[180:181], v[130:131] op_sel_hi:[1,0,1]
	v_pk_fma_f32 v[36:37], v[36:37], v[180:181], v[132:133] op_sel_hi:[1,0,1]
	v_pk_mul_f32 v[42:43], v[34:35], v[42:43]
	v_pk_mul_f32 v[34:35], v[44:45], v[48:49]
	v_pk_fma_f32 v[30:31], v[30:31], v[176:177], v[142:143] op_sel_hi:[1,0,1]
	v_pk_mul_f32 v[44:45], v[36:37], v[34:35]
	v_mad_i64_i32 v[34:35], s[18:19], v178, s56, v[166:167]
	v_lshl_add_u64 v[34:35], v[34:35], 0, s[16:17]
	v_lshl_add_u64 v[46:47], v[34:35], 0, v[154:155]
	v_cvt_pk_bf16_f32 v34, v38, v39
	v_cvt_pk_bf16_f32 v35, v40, v41
	v_cvt_pk_bf16_f32 v36, v42, v43
	v_cvt_pk_bf16_f32 v37, v44, v45
	v_pk_mul_f32 v[38:39], v[30:31], s[20:21] op_sel_hi:[1,0]
	v_pk_fma_f32 v[32:33], v[32:33], v[176:177], v[144:145] op_sel_hi:[1,0,1]
	v_exp_f32_e32 v38, v38
	v_exp_f32_e32 v39, v39
	global_store_dwordx4 v[46:47], v[34:37], off nt
	v_pk_fma_f32 v[22:23], v[22:23], v[176:177], v[138:139] op_sel_hi:[1,0,1]
	v_pk_fma_f32 v[26:27], v[26:27], v[176:177], v[134:135] op_sel_hi:[1,0,1]
	v_pk_mul_f32 v[36:37], v[32:33], s[20:21] op_sel_hi:[1,0]
	v_exp_f32_e32 v36, v36
	v_exp_f32_e32 v37, v37
	v_pk_add_f32 v[34:35], v[38:39], 1.0 op_sel_hi:[1,0]
	v_rcp_f32_e32 v34, v34
	v_rcp_f32_e32 v35, v35
	v_pk_add_f32 v[36:37], v[36:37], 1.0 op_sel_hi:[1,0]
	v_rcp_f32_e32 v36, v36
	v_rcp_f32_e32 v37, v37
	v_pk_mul_f32 v[30:31], v[30:31], v[34:35]
	v_pk_fma_f32 v[24:25], v[24:25], v[176:177], v[140:141] op_sel_hi:[1,0,1]
	v_pk_mul_f32 v[22:23], v[22:23], v[30:31]
	v_pk_mul_f32 v[30:31], v[32:33], v[36:37]
	v_pk_mul_f32 v[32:33], v[26:27], s[20:21] op_sel_hi:[1,0]
	v_exp_f32_e32 v32, v32
	v_exp_f32_e32 v33, v33
	v_pk_fma_f32 v[28:29], v[28:29], v[176:177], v[136:137] op_sel_hi:[1,0,1]
	v_pk_mul_f32 v[24:25], v[24:25], v[30:31]
	v_pk_add_f32 v[30:31], v[32:33], 1.0 op_sel_hi:[1,0]
	v_pk_mul_f32 v[32:33], v[28:29], s[20:21] op_sel_hi:[1,0]
	v_exp_f32_e32 v32, v32
	v_exp_f32_e32 v33, v33
	v_rcp_f32_e32 v30, v30
	v_rcp_f32_e32 v31, v31
	v_pk_add_f32 v[32:33], v[32:33], 1.0 op_sel_hi:[1,0]
	v_rcp_f32_e32 v32, v32
	v_rcp_f32_e32 v33, v33
	v_pk_mul_f32 v[26:27], v[26:27], v[30:31]
	v_pk_fma_f32 v[18:19], v[18:19], v[176:177], v[130:131] op_sel_hi:[1,0,1]
	v_pk_fma_f32 v[20:21], v[20:21], v[176:177], v[132:133] op_sel_hi:[1,0,1]
	v_pk_mul_f32 v[26:27], v[18:19], v[26:27]
	v_pk_mul_f32 v[18:19], v[28:29], v[32:33]
	v_pk_fma_f32 v[14:15], v[14:15], v[172:173], v[142:143] op_sel_hi:[1,0,1]
	v_pk_mul_f32 v[28:29], v[20:21], v[18:19]
	v_mad_i64_i32 v[18:19], s[18:19], v174, s56, v[166:167]
	v_lshl_add_u64 v[18:19], v[18:19], 0, s[16:17]
	v_lshl_add_u64 v[30:31], v[18:19], 0, v[154:155]
	v_cvt_pk_bf16_f32 v18, v22, v23
	v_cvt_pk_bf16_f32 v19, v24, v25
	v_cvt_pk_bf16_f32 v20, v26, v27
	v_cvt_pk_bf16_f32 v21, v28, v29
	v_pk_mul_f32 v[22:23], v[14:15], s[20:21] op_sel_hi:[1,0]
	v_pk_fma_f32 v[16:17], v[16:17], v[172:173], v[144:145] op_sel_hi:[1,0,1]
	v_exp_f32_e32 v22, v22
	v_exp_f32_e32 v23, v23
	global_store_dwordx4 v[30:31], v[18:21], off nt
	v_pk_fma_f32 v[6:7], v[6:7], v[172:173], v[138:139] op_sel_hi:[1,0,1]
	v_pk_fma_f32 v[10:11], v[10:11], v[172:173], v[134:135] op_sel_hi:[1,0,1]
	v_pk_mul_f32 v[20:21], v[16:17], s[20:21] op_sel_hi:[1,0]
	v_exp_f32_e32 v20, v20
	v_exp_f32_e32 v21, v21
	v_pk_add_f32 v[18:19], v[22:23], 1.0 op_sel_hi:[1,0]
	v_rcp_f32_e32 v18, v18
	v_rcp_f32_e32 v19, v19
	v_pk_add_f32 v[20:21], v[20:21], 1.0 op_sel_hi:[1,0]
	v_rcp_f32_e32 v20, v20
	v_rcp_f32_e32 v21, v21
	v_pk_mul_f32 v[14:15], v[14:15], v[18:19]
	v_pk_fma_f32 v[8:9], v[8:9], v[172:173], v[140:141] op_sel_hi:[1,0,1]
	v_pk_mul_f32 v[6:7], v[6:7], v[14:15]
	v_pk_mul_f32 v[14:15], v[16:17], v[20:21]
	v_pk_mul_f32 v[16:17], v[10:11], s[20:21] op_sel_hi:[1,0]
	v_exp_f32_e32 v16, v16
	v_exp_f32_e32 v17, v17
	v_pk_fma_f32 v[12:13], v[12:13], v[172:173], v[136:137] op_sel_hi:[1,0,1]
	v_pk_mul_f32 v[8:9], v[8:9], v[14:15]
	v_pk_add_f32 v[14:15], v[16:17], 1.0 op_sel_hi:[1,0]
	v_pk_mul_f32 v[16:17], v[12:13], s[20:21] op_sel_hi:[1,0]
	v_exp_f32_e32 v16, v16
	v_exp_f32_e32 v17, v17
	v_rcp_f32_e32 v14, v14
	v_rcp_f32_e32 v15, v15
	v_pk_add_f32 v[16:17], v[16:17], 1.0 op_sel_hi:[1,0]
	v_rcp_f32_e32 v16, v16
	v_rcp_f32_e32 v17, v17
	v_pk_mul_f32 v[10:11], v[10:11], v[14:15]
	v_pk_fma_f32 v[2:3], v[2:3], v[172:173], v[130:131] op_sel_hi:[1,0,1]
	v_pk_fma_f32 v[4:5], v[4:5], v[172:173], v[132:133] op_sel_hi:[1,0,1]
	v_pk_mul_f32 v[10:11], v[2:3], v[10:11]
	v_pk_mul_f32 v[2:3], v[12:13], v[16:17]
	s_nop 0
	v_pk_mul_f32 v[12:13], v[4:5], v[2:3]
	v_mad_i64_i32 v[2:3], s[18:19], v168, s56, v[166:167]
	v_lshl_add_u64 v[2:3], v[2:3], 0, s[16:17]
	v_lshl_add_u64 v[14:15], v[2:3], 0, v[154:155]
	v_cvt_pk_bf16_f32 v2, v6, v7
	v_cvt_pk_bf16_f32 v3, v8, v9
	v_cvt_pk_bf16_f32 v4, v10, v11
	v_cvt_pk_bf16_f32 v5, v12, v13
	s_mov_b32 s17, s8
	s_mov_b32 s16, s10
	global_store_dwordx4 v[14:15], v[2:5], off nt
	s_cmpk_gt_u32 s33, 0xff
	s_cbranch_scc0 .Ldfr_p12_c
	s_barrier
